# speedup vs baseline: 1.0267x; 1.0017x over previous
; template <int MODE> ...
;     ...
;                 float sacc = 0.f;
; #pragma unroll
;                 for (int r = 0; r < 16; ++r) { p0[r] = ex2(p0[r] - mhat); p1[r] = ex2(p1[r] - mhat); sacc += p0[r] + p1[r]; }
;                 lsum += sacc;
;             } else {
;                 f32x16 L0, L1;
; #pragma unroll
;                 for (int r = 0; r < 16; ++r) {
;                     const float s0 = p0[r], s1 = p1[r];
;                     float l0 = lg2(1.0f + ex2(s0)), l1 = lg2(1.0f + ex2(s1));
;                     l0 = s0 > 32.f ? s0 : l0; l1 = s1 > 32.f ? s1 : l1;
;                     float g0 = s0 - l0, g1 = s1 - l1;
;                     if (!full) { const int k0 = crow(r, hi_m), k1 = k0 + 32; if (!(k0 < dq)) { l0 = 0.f; g0 = -INFINITY; } if (!(k1 < dq)) { l1 = 0.f; g1 = -INFINITY; } }
;                     L0[r] = l0; L1[r] = l1; p0[r] = g0; p1[r] = g1;
;                 }
;                 float T[8], U[8], Tp[8];
; #pragma unroll
;                 for (int g = 0; g < 8; ++g) { const int b = 4 * (g & 3);
;                     const float a0 = g < 4 ? L0[b] : L1[b], a1 = g < 4 ? L0[b + 1] : L1[b + 1], a2 = g < 4 ? L0[b + 2] : L1[b + 2], a3 = g < 4 ? L0[b + 3] : L1[b + 3];
;                     const float s2 = a3 + a2, s1 = s2 + a1; T[g] = s1 + a0;
;                     if (g < 4) { L0[b] = s1; L0[b + 1] = s2; L0[b + 2] = a3; L0[b + 3] = 0.f; } else { L1[b] = s1; L1[b + 1] = s2; L1[b + 2] = a3; L1[b + 3] = 0.f; }
;                     auto rr = __builtin_amdgcn_permlane32_swap(__float_as_uint(T[g]), __float_as_uint(T[g]), false, false);
;                     const float x0 = __uint_as_float(rr[0]), x1 = __uint_as_float(rr[1]);
;                     U[g] = x0 + x1; Tp[g] = hi == 0 ? x1 : 0.f; }
;                 float ss = 0.f;
; #pragma unroll
;                 for (int g = 7; g >= 0; --g) { const int b = 4 * (g & 3); const float base = Rp + ss + Tp[g];
; #pragma unroll
;                     for (int e = 0; e < 4; ++e) { if (g < 4) p0[b + e] = ex2(p0[b + e] - base - L0[b + e]); else p1[b + e] = ex2(p1[b + e] - base - L1[b + e]); }
;                     ss += U[g]; }
;                 Rp += ss;
;             }
;             pw0 = (u32x4){cvtpk(p0[0], p0[1]), cvtpk(p0[2], p0[3]), cvtpk(p0[4], p0[5]), cvtpk(p0[6], p0[7])};
;             pw1 = (u32x4){cvtpk(p0[8], p0[9]), cvtpk(p0[10], p0[11]), cvtpk(p0[12], p0[13]), cvtpk(p0[14], p0[15])};
.LBB0_207:
	v_sub_f32_e32 v0, v50, v132
	v_exp_f32_e32 v85, v0
	v_sub_f32_e32 v0, v34, v132
	v_sub_f32_e32 v34, v35, v132
	v_exp_f32_e32 v84, v34
	v_sub_f32_e32 v34, v52, v132
	v_exp_f32_e32 v87, v0
	v_sub_f32_e32 v0, v51, v132
	v_exp_f32_e32 v51, v34
	v_sub_f32_e32 v34, v36, v132
	v_exp_f32_e32 v89, v34
	v_sub_f32_e32 v34, v53, v132
	v_exp_f32_e32 v50, v34
	v_sub_f32_e32 v34, v37, v132
	v_exp_f32_e32 v86, v34
	v_sub_f32_e32 v34, v54, v132
	v_exp_f32_e32 v53, v34
	v_sub_f32_e32 v34, v38, v132
	v_exp_f32_e32 v91, v34
	v_sub_f32_e32 v34, v55, v132
	v_exp_f32_e32 v52, v34
	v_sub_f32_e32 v34, v39, v132
	v_exp_f32_e32 v88, v34
	v_sub_f32_e32 v34, v56, v132
	v_exp_f32_e32 v55, v34
	v_sub_f32_e32 v34, v40, v132
	v_exp_f32_e32 v93, v34
	v_sub_f32_e32 v34, v57, v132
	v_exp_f32_e32 v54, v34
	v_sub_f32_e32 v34, v41, v132
	v_exp_f32_e32 v90, v34
	v_sub_f32_e32 v34, v58, v132
	v_exp_f32_e32 v57, v34
	v_sub_f32_e32 v34, v42, v132
	v_exp_f32_e32 v95, v34
	v_sub_f32_e32 v34, v59, v132
	v_exp_f32_e32 v56, v34
	v_sub_f32_e32 v34, v43, v132
	v_exp_f32_e32 v92, v34
	v_sub_f32_e32 v34, v60, v132
	v_exp_f32_e32 v59, v34
	v_sub_f32_e32 v34, v44, v132
	v_exp_f32_e32 v97, v34
	v_sub_f32_e32 v34, v61, v132
	v_exp_f32_e32 v58, v34
	v_sub_f32_e32 v34, v45, v132
	v_exp_f32_e32 v94, v34
	v_sub_f32_e32 v34, v62, v132
	v_exp_f32_e32 v61, v34
	v_sub_f32_e32 v34, v46, v132
	v_exp_f32_e32 v133, v34
	v_sub_f32_e32 v34, v63, v132
	v_exp_f32_e32 v60, v34
	v_sub_f32_e32 v34, v47, v132
	v_exp_f32_e32 v96, v34
	v_sub_f32_e32 v34, v64, v132
	v_exp_f32_e32 v63, v34
	v_sub_f32_e32 v34, v48, v132
	v_exp_f32_e32 v134, v34
	v_sub_f32_e32 v34, v65, v132
	v_exp_f32_e32 v62, v34
	v_sub_f32_e32 v34, v49, v132
	v_exp_f32_e32 v0, v0
	v_exp_f32_e32 v64, v34
	s_mul_hi_u32 s4, s39, 0xaaaaaaab
	s_lshr_b32 s4, s4, 1
	v_cvt_pk_bf16_f32 v34, v85, v0
	v_cvt_pk_bf16_f32 v35, v51, v50
	v_cvt_pk_bf16_f32 v36, v53, v52
	v_cvt_pk_bf16_f32 v37, v55, v54
	v_cvt_pk_bf16_f32 v46, v57, v56
	v_cvt_pk_bf16_f32 v47, v59, v58
	v_cvt_pk_bf16_f32 v48, v61, v60
	v_cvt_pk_bf16_f32 v49, v63, v62
	v_cvt_pk_bf16_f32 v38, v87, v84
	v_cvt_pk_bf16_f32 v39, v89, v86
	v_cvt_pk_bf16_f32 v40, v91, v88
	v_cvt_pk_bf16_f32 v41, v93, v90
	v_cvt_pk_bf16_f32 v42, v95, v92
	v_cvt_pk_bf16_f32 v43, v97, v94
	v_cvt_pk_bf16_f32 v44, v133, v96
	s_andn2_b64 vcc, exec, s[12:13]
	v_cvt_pk_bf16_f32 v45, v134, v64
	s_cbranch_vccnz .LBB0_209
	s_mul_i32 s4, s4, 0xffff4000
	v_add_u32_e32 v135, s4, v129
	v_add3_u32 v135, v135, v114, s25
	ds_read_b64_tr_b16 v[136:137], v135
	ds_read_b64_tr_b16 v[138:139], v135 offset:512
	ds_read_b64_tr_b16 v[140:141], v135 offset:1024
	ds_read_b64_tr_b16 v[142:143], v135 offset:1536
	ds_read_b64_tr_b16 v[144:145], v135 offset:2048
	ds_read_b64_tr_b16 v[146:147], v135 offset:2560
	ds_read_b64_tr_b16 v[148:149], v135 offset:3072
	ds_read_b64_tr_b16 v[150:151], v135 offset:3584
	ds_read_b64_tr_b16 v[152:153], v135 offset:4096
	ds_read_b64_tr_b16 v[154:155], v135 offset:4608
	ds_read_b64_tr_b16 v[156:157], v135 offset:5120
	ds_read_b64_tr_b16 v[158:159], v135 offset:5632
	ds_read_b64_tr_b16 v[160:161], v135 offset:6144
	ds_read_b64_tr_b16 v[162:163], v135 offset:6656
	ds_read_b64_tr_b16 v[164:165], v135 offset:7168
	ds_read_b64_tr_b16 v[166:167], v135 offset:7680
	s_waitcnt lgkmcnt(14)
	v_mfma_f32_32x32x16_bf16 v[18:33], v[34:37], v[136:139], v[18:33]
	s_waitcnt lgkmcnt(6)
	v_mfma_f32_32x32x16_bf16 v[2:17], v[34:37], v[152:155], v[2:17]
	v_mfma_f32_32x32x16_bf16 v[18:33], v[46:49], v[140:143], v[18:33]
	s_waitcnt lgkmcnt(4)
	v_mfma_f32_32x32x16_bf16 v[2:17], v[46:49], v[156:159], v[2:17]
	v_mfma_f32_32x32x16_bf16 v[18:33], v[38:41], v[144:147], v[18:33]
	s_waitcnt lgkmcnt(2)
	v_mfma_f32_32x32x16_bf16 v[2:17], v[38:41], v[160:163], v[2:17]
	v_mfma_f32_32x32x16_bf16 v[18:33], v[42:45], v[148:151], v[18:33]
	s_waitcnt lgkmcnt(0)
	v_mfma_f32_32x32x16_bf16 v[2:17], v[42:45], v[164:167], v[2:17]
	s_branch .LBB0_210
